# removed the per-MFMA-block s_setprio 1/0 toggles from the four GEMM K-loops (64 instructions)
# baseline (speedup 1.0000x reference)
.LBB0_320:
	ds_read_b128 v[128:131], v180
	ds_read_b128 v[132:135], v180 offset:1024
	ds_read_b128 v[136:139], v180 offset:2048
	ds_read_b128 v[162:165], v180 offset:3072
	ds_read_b128 v[166:169], v181
	ds_read_b128 v[170:173], v181 offset:1024
	ds_read_b128 v[174:177], v181 offset:2048
	ds_read_b128 v[188:191], v181 offset:3072
	s_add_u32 s54, s68, 0xfff80080
	s_addc_u32 s55, s69, -1
	s_cmp_eq_u32 s87, 28
	s_cselect_b32 s73, s63, s55
	s_cselect_b32 s72, s96, s54
	s_cselect_b32 s71, s59, vcc_hi
	s_cselect_b32 s70, s97, vcc_lo
	v_lshl_add_u64 v[226:227], s[68:69], 0, v[154:155]
	s_add_i32 m0, s76, 0xc000
	ds_read_b128 v[192:195], v182
	ds_read_b128 v[196:199], v182 offset:1024
	ds_read_b128 v[200:203], v182 offset:2048
	ds_read_b128 v[204:207], v182 offset:3072
	ds_read_b128 v[210:213], v182 offset:4096
	ds_read_b128 v[214:217], v182 offset:5120
	ds_read_b128 v[218:221], v182 offset:6144
	ds_read_b128 v[222:225], v182 offset:7168
	global_load_lds_dwordx4 v[226:227], off
	v_lshl_add_u64 v[226:227], s[68:69], 0, v[156:157]
	s_add_i32 m0, s76, 0xe000
	s_nop 0
	global_load_lds_dwordx4 v[226:227], off
	s_waitcnt vmcnt(8)
	s_waitcnt lgkmcnt(0)
	s_barrier
	s_waitcnt lgkmcnt(0)
	v_mfma_f32_16x16x32_bf16 v[124:127], v[128:131], v[192:195], v[124:127]
	v_mfma_f32_16x16x32_bf16 v[116:119], v[136:139], v[192:195], v[116:119]
	v_mfma_f32_16x16x32_bf16 v[108:111], v[128:131], v[200:203], v[108:111]
	v_mfma_f32_16x16x32_bf16 v[100:103], v[136:139], v[200:203], v[100:103]
	v_mfma_f32_16x16x32_bf16 v[92:95], v[128:131], v[210:213], v[92:95]
	v_mfma_f32_16x16x32_bf16 v[84:87], v[136:139], v[210:213], v[84:87]
	v_mfma_f32_16x16x32_bf16 v[76:79], v[128:131], v[218:221], v[76:79]
	v_mfma_f32_16x16x32_bf16 v[68:71], v[136:139], v[218:221], v[68:71]
	v_mfma_f32_16x16x32_bf16 v[124:127], v[132:135], v[196:199], v[124:127]
	v_mfma_f32_16x16x32_bf16 v[116:119], v[162:165], v[196:199], v[116:119]
	v_mfma_f32_16x16x32_bf16 v[108:111], v[132:135], v[204:207], v[108:111]
	v_mfma_f32_16x16x32_bf16 v[100:103], v[162:165], v[204:207], v[100:103]
	v_mfma_f32_16x16x32_bf16 v[92:95], v[132:135], v[214:217], v[92:95]
	v_mfma_f32_16x16x32_bf16 v[84:87], v[162:165], v[214:217], v[84:87]
	v_mfma_f32_16x16x32_bf16 v[76:79], v[132:135], v[222:225], v[76:79]
	v_mfma_f32_16x16x32_bf16 v[68:71], v[162:165], v[222:225], v[68:71]
	v_mfma_f32_16x16x32_bf16 v[120:123], v[166:169], v[192:195], v[120:123]
	v_mfma_f32_16x16x32_bf16 v[112:115], v[174:177], v[192:195], v[112:115]
	v_mfma_f32_16x16x32_bf16 v[104:107], v[166:169], v[200:203], v[104:107]
	v_mfma_f32_16x16x32_bf16 v[96:99], v[174:177], v[200:203], v[96:99]
	v_mfma_f32_16x16x32_bf16 v[88:91], v[166:169], v[210:213], v[88:91]
	v_mfma_f32_16x16x32_bf16 v[80:83], v[174:177], v[210:213], v[80:83]
	v_mfma_f32_16x16x32_bf16 v[72:75], v[166:169], v[218:221], v[72:75]
	v_mfma_f32_16x16x32_bf16 v[64:67], v[174:177], v[218:221], v[64:67]
	v_mfma_f32_16x16x32_bf16 v[120:123], v[170:173], v[196:199], v[120:123]
	v_mfma_f32_16x16x32_bf16 v[112:115], v[188:191], v[196:199], v[112:115]
	v_mfma_f32_16x16x32_bf16 v[104:107], v[170:173], v[204:207], v[104:107]
	v_mfma_f32_16x16x32_bf16 v[96:99], v[188:191], v[204:207], v[96:99]
	v_mfma_f32_16x16x32_bf16 v[88:91], v[170:173], v[214:217], v[88:91]
	v_mfma_f32_16x16x32_bf16 v[80:83], v[188:191], v[214:217], v[80:83]
	v_mfma_f32_16x16x32_bf16 v[72:75], v[170:173], v[222:225], v[72:75]
	v_mfma_f32_16x16x32_bf16 v[64:67], v[188:191], v[222:225], v[64:67]
	s_barrier
	s_add_i32 s54, s82, s74
	v_lshl_add_u64 v[226:227], s[70:71], 0, v[146:147]
	s_mov_b32 m0, s54
	ds_read_b128 v[192:195], v182 offset:16384
	ds_read_b128 v[196:199], v182 offset:17408
	ds_read_b128 v[200:203], v182 offset:18432
	ds_read_b128 v[204:207], v182 offset:19456
	ds_read_b128 v[210:213], v182 offset:20480
	ds_read_b128 v[214:217], v182 offset:21504
	ds_read_b128 v[218:221], v182 offset:22528
	ds_read_b128 v[222:225], v182 offset:23552
	global_load_lds_dwordx4 v[226:227], off
	s_add_i32 m0, s54, 0x2000
	s_add_u32 s54, s70, 0x80000
	v_lshl_add_u64 v[228:229], s[70:71], 0, v[142:143]
	s_addc_u32 s55, s71, 0
	s_add_i32 s88, s83, s74
	global_load_lds_dwordx4 v[228:229], off
	v_lshl_add_u64 v[230:231], s[54:55], 0, v[146:147]
	s_mov_b32 m0, s88
	v_lshl_add_u64 v[232:233], s[72:73], 0, v[144:145]
	global_load_lds_dwordx4 v[230:231], off
	v_lshl_add_u64 v[230:231], s[54:55], 0, v[142:143]
	s_add_i32 m0, s88, 0x2000
	s_nop 0
	global_load_lds_dwordx4 v[230:231], off
	v_lshl_add_u64 v[230:231], s[72:73], 0, v[148:149]
	s_mov_b32 m0, s76
	s_nop 0
	global_load_lds_dwordx4 v[230:231], off
	s_mov_b32 m0, s77
	s_nop 0
	global_load_lds_dwordx4 v[232:233], off
	s_waitcnt vmcnt(8)
	s_waitcnt lgkmcnt(0)
	s_barrier
	s_waitcnt lgkmcnt(0)
	v_mfma_f32_16x16x32_bf16 v[60:63], v[128:131], v[192:195], v[60:63]
	v_mfma_f32_16x16x32_bf16 v[52:55], v[136:139], v[192:195], v[52:55]
	v_mfma_f32_16x16x32_bf16 v[44:47], v[128:131], v[200:203], v[44:47]
	v_mfma_f32_16x16x32_bf16 v[36:39], v[136:139], v[200:203], v[36:39]
	v_mfma_f32_16x16x32_bf16 v[28:31], v[128:131], v[210:213], v[28:31]
	v_mfma_f32_16x16x32_bf16 v[20:23], v[136:139], v[210:213], v[20:23]
	v_mfma_f32_16x16x32_bf16 v[12:15], v[128:131], v[218:221], v[12:15]
	v_mfma_f32_16x16x32_bf16 v[4:7], v[136:139], v[218:221], v[4:7]
	v_mfma_f32_16x16x32_bf16 v[60:63], v[132:135], v[196:199], v[60:63]
	v_mfma_f32_16x16x32_bf16 v[52:55], v[162:165], v[196:199], v[52:55]
	v_mfma_f32_16x16x32_bf16 v[44:47], v[132:135], v[204:207], v[44:47]
	v_mfma_f32_16x16x32_bf16 v[36:39], v[162:165], v[204:207], v[36:39]
	v_mfma_f32_16x16x32_bf16 v[28:31], v[132:135], v[214:217], v[28:31]
	v_mfma_f32_16x16x32_bf16 v[20:23], v[162:165], v[214:217], v[20:23]
	v_mfma_f32_16x16x32_bf16 v[12:15], v[132:135], v[222:225], v[12:15]
	v_mfma_f32_16x16x32_bf16 v[4:7], v[162:165], v[222:225], v[4:7]
	v_mfma_f32_16x16x32_bf16 v[56:59], v[166:169], v[192:195], v[56:59]
	v_mfma_f32_16x16x32_bf16 v[48:51], v[174:177], v[192:195], v[48:51]
	v_mfma_f32_16x16x32_bf16 v[40:43], v[166:169], v[200:203], v[40:43]
	v_mfma_f32_16x16x32_bf16 v[32:35], v[174:177], v[200:203], v[32:35]
	v_mfma_f32_16x16x32_bf16 v[24:27], v[166:169], v[210:213], v[24:27]
	v_mfma_f32_16x16x32_bf16 v[16:19], v[174:177], v[210:213], v[16:19]
	v_mfma_f32_16x16x32_bf16 v[8:11], v[166:169], v[218:221], v[8:11]
	v_mfma_f32_16x16x32_bf16 v[0:3], v[174:177], v[218:221], v[0:3]
	v_mfma_f32_16x16x32_bf16 v[56:59], v[170:173], v[196:199], v[56:59]
	v_mfma_f32_16x16x32_bf16 v[48:51], v[188:191], v[196:199], v[48:51]
	v_mfma_f32_16x16x32_bf16 v[40:43], v[170:173], v[204:207], v[40:43]
	v_mfma_f32_16x16x32_bf16 v[32:35], v[188:191], v[204:207], v[32:35]
	v_mfma_f32_16x16x32_bf16 v[24:27], v[170:173], v[214:217], v[24:27]
	v_mfma_f32_16x16x32_bf16 v[16:19], v[188:191], v[214:217], v[16:19]
	v_mfma_f32_16x16x32_bf16 v[8:11], v[170:173], v[222:225], v[8:11]
	v_mfma_f32_16x16x32_bf16 v[0:3], v[188:191], v[222:225], v[0:3]
	s_barrier
	s_add_i32 s88, 0, 0x18000
	v_add_u32_e32 v150, s88, v178
	s_add_i32 s86, 0, 0x1c000
	ds_read_b128 v[128:131], v150
	ds_read_b128 v[132:135], v150 offset:1024
	ds_read_b128 v[136:139], v150 offset:2048
	ds_read_b128 v[162:165], v150 offset:3072
	v_add_u32_e32 v150, s86, v178
	ds_read_b128 v[166:169], v150
	ds_read_b128 v[170:173], v150 offset:1024
	ds_read_b128 v[174:177], v150 offset:2048
	ds_read_b128 v[188:191], v150 offset:3072
	s_add_u32 s54, s72, 0x80000
	s_addc_u32 s55, s73, 0
	s_mov_b32 m0, s78
	v_lshl_add_u64 v[234:235], s[54:55], 0, v[148:149]
	ds_read_b128 v[192:195], v182 offset:32768
	ds_read_b128 v[196:199], v182 offset:33792
	ds_read_b128 v[200:203], v182 offset:34816
	ds_read_b128 v[204:207], v182 offset:35840
	ds_read_b128 v[210:213], v182 offset:36864
	ds_read_b128 v[214:217], v182 offset:37888
	ds_read_b128 v[218:221], v182 offset:38912
	ds_read_b128 v[222:225], v182 offset:39936
	global_load_lds_dwordx4 v[234:235], off
	v_lshl_add_u64 v[234:235], s[54:55], 0, v[144:145]
	s_mov_b32 m0, s79
	s_nop 0
	global_load_lds_dwordx4 v[234:235], off
	s_waitcnt vmcnt(8)
	s_waitcnt lgkmcnt(0)
	s_barrier
	s_waitcnt lgkmcnt(0)
	v_mfma_f32_16x16x32_bf16 v[124:127], v[128:131], v[192:195], v[124:127]
	v_mfma_f32_16x16x32_bf16 v[116:119], v[136:139], v[192:195], v[116:119]
	v_mfma_f32_16x16x32_bf16 v[108:111], v[128:131], v[200:203], v[108:111]
	v_mfma_f32_16x16x32_bf16 v[100:103], v[136:139], v[200:203], v[100:103]
	v_mfma_f32_16x16x32_bf16 v[92:95], v[128:131], v[210:213], v[92:95]
	v_mfma_f32_16x16x32_bf16 v[84:87], v[136:139], v[210:213], v[84:87]
	v_mfma_f32_16x16x32_bf16 v[76:79], v[128:131], v[218:221], v[76:79]
	v_mfma_f32_16x16x32_bf16 v[68:71], v[136:139], v[218:221], v[68:71]
	v_mfma_f32_16x16x32_bf16 v[124:127], v[132:135], v[196:199], v[124:127]
	v_mfma_f32_16x16x32_bf16 v[116:119], v[162:165], v[196:199], v[116:119]
	v_mfma_f32_16x16x32_bf16 v[108:111], v[132:135], v[204:207], v[108:111]
	v_mfma_f32_16x16x32_bf16 v[100:103], v[162:165], v[204:207], v[100:103]
	v_mfma_f32_16x16x32_bf16 v[92:95], v[132:135], v[214:217], v[92:95]
	v_mfma_f32_16x16x32_bf16 v[84:87], v[162:165], v[214:217], v[84:87]
	v_mfma_f32_16x16x32_bf16 v[76:79], v[132:135], v[222:225], v[76:79]
	v_mfma_f32_16x16x32_bf16 v[68:71], v[162:165], v[222:225], v[68:71]
	v_mfma_f32_16x16x32_bf16 v[120:123], v[166:169], v[192:195], v[120:123]
	v_mfma_f32_16x16x32_bf16 v[112:115], v[174:177], v[192:195], v[112:115]
	v_mfma_f32_16x16x32_bf16 v[104:107], v[166:169], v[200:203], v[104:107]
	v_mfma_f32_16x16x32_bf16 v[96:99], v[174:177], v[200:203], v[96:99]
	v_mfma_f32_16x16x32_bf16 v[88:91], v[166:169], v[210:213], v[88:91]
	v_mfma_f32_16x16x32_bf16 v[80:83], v[174:177], v[210:213], v[80:83]
	v_mfma_f32_16x16x32_bf16 v[72:75], v[166:169], v[218:221], v[72:75]
	v_mfma_f32_16x16x32_bf16 v[64:67], v[174:177], v[218:221], v[64:67]
	v_mfma_f32_16x16x32_bf16 v[120:123], v[170:173], v[196:199], v[120:123]
	v_mfma_f32_16x16x32_bf16 v[112:115], v[188:191], v[196:199], v[112:115]
	v_mfma_f32_16x16x32_bf16 v[104:107], v[170:173], v[204:207], v[104:107]
	v_mfma_f32_16x16x32_bf16 v[96:99], v[188:191], v[204:207], v[96:99]
	v_mfma_f32_16x16x32_bf16 v[88:91], v[170:173], v[214:217], v[88:91]
	v_mfma_f32_16x16x32_bf16 v[80:83], v[188:191], v[214:217], v[80:83]
	v_mfma_f32_16x16x32_bf16 v[72:75], v[170:173], v[222:225], v[72:75]
	v_mfma_f32_16x16x32_bf16 v[64:67], v[188:191], v[222:225], v[64:67]
	s_barrier
	s_add_i32 s54, s88, s74
	v_lshl_add_u64 v[226:227], v[226:227], 0, s[40:41]
	s_mov_b32 m0, s54
	ds_read_b128 v[192:195], v182 offset:49152
	ds_read_b128 v[196:199], v182 offset:50176
	ds_read_b128 v[200:203], v182 offset:51200
	ds_read_b128 v[204:207], v182 offset:52224
	ds_read_b128 v[210:213], v182 offset:53248
	ds_read_b128 v[214:217], v182 offset:54272
	ds_read_b128 v[218:221], v182 offset:55296
	ds_read_b128 v[222:225], v182 offset:56320
	global_load_lds_dwordx4 v[226:227], off
	s_add_i32 m0, s54, 0x2000
	s_add_u32 s54, s70, 0x80080
	v_lshl_add_u64 v[226:227], v[228:229], 0, s[40:41]
	s_addc_u32 s55, s71, 0
	s_add_i32 s70, s86, s74
	global_load_lds_dwordx4 v[226:227], off
	v_lshl_add_u64 v[226:227], s[54:55], 0, v[146:147]
	s_mov_b32 m0, s70
	s_nop 0
	global_load_lds_dwordx4 v[226:227], off
	v_lshl_add_u64 v[226:227], s[54:55], 0, v[142:143]
	s_add_i32 m0, s70, 0x2000
	s_nop 0
	global_load_lds_dwordx4 v[226:227], off
	v_lshl_add_u64 v[226:227], v[230:231], 0, s[40:41]
	s_mov_b32 m0, s80
	s_nop 0
	global_load_lds_dwordx4 v[226:227], off
	v_lshl_add_u64 v[226:227], v[232:233], 0, s[40:41]
	s_mov_b32 m0, s81
	s_nop 0
	global_load_lds_dwordx4 v[226:227], off
	s_waitcnt vmcnt(8)
	s_waitcnt lgkmcnt(0)
	s_barrier
	s_waitcnt lgkmcnt(0)
	v_mfma_f32_16x16x32_bf16 v[60:63], v[128:131], v[192:195], v[60:63]
	v_mfma_f32_16x16x32_bf16 v[52:55], v[136:139], v[192:195], v[52:55]
	v_mfma_f32_16x16x32_bf16 v[44:47], v[128:131], v[200:203], v[44:47]
	v_mfma_f32_16x16x32_bf16 v[36:39], v[136:139], v[200:203], v[36:39]
	v_mfma_f32_16x16x32_bf16 v[28:31], v[128:131], v[210:213], v[28:31]
	v_mfma_f32_16x16x32_bf16 v[20:23], v[136:139], v[210:213], v[20:23]
	v_mfma_f32_16x16x32_bf16 v[12:15], v[128:131], v[218:221], v[12:15]
	v_mfma_f32_16x16x32_bf16 v[4:7], v[136:139], v[218:221], v[4:7]
	v_mfma_f32_16x16x32_bf16 v[60:63], v[132:135], v[196:199], v[60:63]
	v_mfma_f32_16x16x32_bf16 v[52:55], v[162:165], v[196:199], v[52:55]
	v_mfma_f32_16x16x32_bf16 v[44:47], v[132:135], v[204:207], v[44:47]
	v_mfma_f32_16x16x32_bf16 v[36:39], v[162:165], v[204:207], v[36:39]
	v_mfma_f32_16x16x32_bf16 v[28:31], v[132:135], v[214:217], v[28:31]
	v_mfma_f32_16x16x32_bf16 v[20:23], v[162:165], v[214:217], v[20:23]
	v_mfma_f32_16x16x32_bf16 v[12:15], v[132:135], v[222:225], v[12:15]
	v_mfma_f32_16x16x32_bf16 v[4:7], v[162:165], v[222:225], v[4:7]
	v_mfma_f32_16x16x32_bf16 v[56:59], v[166:169], v[192:195], v[56:59]
	v_mfma_f32_16x16x32_bf16 v[48:51], v[174:177], v[192:195], v[48:51]
	v_mfma_f32_16x16x32_bf16 v[40:43], v[166:169], v[200:203], v[40:43]
	v_mfma_f32_16x16x32_bf16 v[32:35], v[174:177], v[200:203], v[32:35]
	v_mfma_f32_16x16x32_bf16 v[24:27], v[166:169], v[210:213], v[24:27]
	v_mfma_f32_16x16x32_bf16 v[16:19], v[174:177], v[210:213], v[16:19]
	v_mfma_f32_16x16x32_bf16 v[8:11], v[166:169], v[218:221], v[8:11]
	v_mfma_f32_16x16x32_bf16 v[0:3], v[174:177], v[218:221], v[0:3]
	v_mfma_f32_16x16x32_bf16 v[56:59], v[170:173], v[196:199], v[56:59]
	v_mfma_f32_16x16x32_bf16 v[48:51], v[188:191], v[196:199], v[48:51]
	v_mfma_f32_16x16x32_bf16 v[40:43], v[170:173], v[204:207], v[40:43]
	v_mfma_f32_16x16x32_bf16 v[32:35], v[188:191], v[204:207], v[32:35]
	v_mfma_f32_16x16x32_bf16 v[24:27], v[170:173], v[214:217], v[24:27]
	v_mfma_f32_16x16x32_bf16 v[16:19], v[188:191], v[214:217], v[16:19]
	v_mfma_f32_16x16x32_bf16 v[8:11], v[170:173], v[222:225], v[8:11]
	v_mfma_f32_16x16x32_bf16 v[0:3], v[188:191], v[222:225], v[0:3]
	s_barrier
	s_add_i32 s87, s87, 2
	s_add_u32 s68, s68, 0x100
	s_addc_u32 s69, s69, 0
	s_add_u32 vcc_lo, vcc_lo, 0x100
	s_addc_u32 vcc_hi, vcc_hi, 0
	s_cmp_gt_u32 s87, 29
	s_cbranch_scc0 .LBB0_320
	s_and_b64 vcc, exec, s[60:61]
	s_cbranch_vccz .LBB0_323
	s_barrier

.LBB0_545:
	ds_read_b128 v[140:143], v147
	ds_read_b128 v[152:155], v147 offset:1024
	ds_read_b128 v[156:159], v147 offset:2048
	ds_read_b128 v[160:163], v147 offset:3072
	ds_read_b128 v[164:167], v148
	ds_read_b128 v[168:171], v148 offset:1024
	ds_read_b128 v[172:175], v148 offset:2048
	ds_read_b128 v[176:179], v148 offset:3072
	s_add_u32 s56, s54, 0xfff80080
	s_addc_u32 s57, s55, -1
	s_cmp_eq_u32 s76, 28
	s_cselect_b32 s59, s45, s57
	s_cselect_b32 s58, s51, s56
	s_cselect_b32 s57, s43, s75
	s_cselect_b32 s56, s73, s74
	v_lshl_add_u64 v[214:215], s[54:55], 0, v[132:133]
	s_add_i32 m0, s60, 0xc000
	ds_read_b128 v[180:183], v149
	ds_read_b128 v[184:187], v149 offset:1024
	ds_read_b128 v[188:191], v149 offset:2048
	ds_read_b128 v[192:195], v149 offset:3072
	ds_read_b128 v[196:199], v149 offset:4096
	ds_read_b128 v[200:203], v149 offset:5120
	ds_read_b128 v[204:207], v149 offset:6144
	ds_read_b128 v[210:213], v149 offset:7168
	global_load_lds_dwordx4 v[214:215], off
	v_lshl_add_u64 v[214:215], s[54:55], 0, v[134:135]
	s_add_i32 m0, s60, 0xe000
	s_nop 0
	global_load_lds_dwordx4 v[214:215], off
	s_waitcnt vmcnt(8)
	s_waitcnt lgkmcnt(0)
	s_barrier
	s_waitcnt lgkmcnt(0)
	v_mfma_f32_16x16x32_bf16 v[124:127], v[140:143], v[180:183], v[124:127]
	v_mfma_f32_16x16x32_bf16 v[120:123], v[156:159], v[180:183], v[120:123]
	v_mfma_f32_16x16x32_bf16 v[108:111], v[140:143], v[188:191], v[108:111]
	v_mfma_f32_16x16x32_bf16 v[104:107], v[156:159], v[188:191], v[104:107]
	v_mfma_f32_16x16x32_bf16 v[92:95], v[140:143], v[196:199], v[92:95]
	v_mfma_f32_16x16x32_bf16 v[88:91], v[156:159], v[196:199], v[88:91]
	v_mfma_f32_16x16x32_bf16 v[76:79], v[140:143], v[204:207], v[76:79]
	v_mfma_f32_16x16x32_bf16 v[72:75], v[156:159], v[204:207], v[72:75]
	v_mfma_f32_16x16x32_bf16 v[124:127], v[152:155], v[184:187], v[124:127]
	v_mfma_f32_16x16x32_bf16 v[120:123], v[160:163], v[184:187], v[120:123]
	v_mfma_f32_16x16x32_bf16 v[108:111], v[152:155], v[192:195], v[108:111]
	v_mfma_f32_16x16x32_bf16 v[104:107], v[160:163], v[192:195], v[104:107]
	v_mfma_f32_16x16x32_bf16 v[92:95], v[152:155], v[200:203], v[92:95]
	v_mfma_f32_16x16x32_bf16 v[88:91], v[160:163], v[200:203], v[88:91]
	v_mfma_f32_16x16x32_bf16 v[76:79], v[152:155], v[210:213], v[76:79]
	v_mfma_f32_16x16x32_bf16 v[72:75], v[160:163], v[210:213], v[72:75]
	v_mfma_f32_16x16x32_bf16 v[116:119], v[164:167], v[180:183], v[116:119]
	v_mfma_f32_16x16x32_bf16 v[112:115], v[172:175], v[180:183], v[112:115]
	v_mfma_f32_16x16x32_bf16 v[100:103], v[164:167], v[188:191], v[100:103]
	v_mfma_f32_16x16x32_bf16 v[96:99], v[172:175], v[188:191], v[96:99]
	v_mfma_f32_16x16x32_bf16 v[84:87], v[164:167], v[196:199], v[84:87]
	v_mfma_f32_16x16x32_bf16 v[80:83], v[172:175], v[196:199], v[80:83]
	v_mfma_f32_16x16x32_bf16 v[68:71], v[164:167], v[204:207], v[68:71]
	v_mfma_f32_16x16x32_bf16 v[64:67], v[172:175], v[204:207], v[64:67]
	v_mfma_f32_16x16x32_bf16 v[116:119], v[168:171], v[184:187], v[116:119]
	v_mfma_f32_16x16x32_bf16 v[112:115], v[176:179], v[184:187], v[112:115]
	v_mfma_f32_16x16x32_bf16 v[100:103], v[168:171], v[192:195], v[100:103]
	v_mfma_f32_16x16x32_bf16 v[96:99], v[176:179], v[192:195], v[96:99]
	v_mfma_f32_16x16x32_bf16 v[84:87], v[168:171], v[200:203], v[84:87]
	v_mfma_f32_16x16x32_bf16 v[80:83], v[176:179], v[200:203], v[80:83]
	v_mfma_f32_16x16x32_bf16 v[68:71], v[168:171], v[210:213], v[68:71]
	v_mfma_f32_16x16x32_bf16 v[64:67], v[176:179], v[210:213], v[64:67]
	s_barrier
	s_add_i32 s77, s70, s3
	v_lshl_add_u64 v[214:215], s[56:57], 0, v[128:129]
	s_mov_b32 m0, s77
	ds_read_b128 v[180:183], v149 offset:16384
	ds_read_b128 v[184:187], v149 offset:17408
	ds_read_b128 v[188:191], v149 offset:18432
	ds_read_b128 v[192:195], v149 offset:19456
	ds_read_b128 v[196:199], v149 offset:20480
	ds_read_b128 v[200:203], v149 offset:21504
	ds_read_b128 v[204:207], v149 offset:22528
	ds_read_b128 v[210:213], v149 offset:23552
	global_load_lds_dwordx4 v[214:215], off
	s_add_i32 m0, s77, 0x2000
	s_add_u32 s78, s56, 0x80000
	v_lshl_add_u64 v[216:217], s[56:57], 0, v[130:131]
	s_addc_u32 s79, s57, 0
	s_add_i32 s77, s71, s3
	global_load_lds_dwordx4 v[216:217], off
	v_lshl_add_u64 v[218:219], s[78:79], 0, v[128:129]
	s_mov_b32 m0, s77
	v_lshl_add_u64 v[220:221], s[58:59], 0, v[130:131]
	global_load_lds_dwordx4 v[218:219], off
	v_lshl_add_u64 v[218:219], s[78:79], 0, v[130:131]
	s_add_i32 m0, s77, 0x2000
	s_nop 0
	global_load_lds_dwordx4 v[218:219], off
	v_lshl_add_u64 v[218:219], s[58:59], 0, v[128:129]
	s_mov_b32 m0, s60
	s_nop 0
	global_load_lds_dwordx4 v[218:219], off
	s_mov_b32 m0, s61
	s_nop 0
	global_load_lds_dwordx4 v[220:221], off
	s_waitcnt vmcnt(8)
	s_waitcnt lgkmcnt(0)
	s_barrier
	s_waitcnt lgkmcnt(0)
	v_mfma_f32_16x16x32_bf16 v[60:63], v[140:143], v[180:183], v[60:63]
	v_mfma_f32_16x16x32_bf16 v[56:59], v[156:159], v[180:183], v[56:59]
	v_mfma_f32_16x16x32_bf16 v[44:47], v[140:143], v[188:191], v[44:47]
	v_mfma_f32_16x16x32_bf16 v[40:43], v[156:159], v[188:191], v[40:43]
	v_mfma_f32_16x16x32_bf16 v[28:31], v[140:143], v[196:199], v[28:31]
	v_mfma_f32_16x16x32_bf16 v[24:27], v[156:159], v[196:199], v[24:27]
	v_mfma_f32_16x16x32_bf16 v[12:15], v[140:143], v[204:207], v[12:15]
	v_mfma_f32_16x16x32_bf16 v[8:11], v[156:159], v[204:207], v[8:11]
	v_mfma_f32_16x16x32_bf16 v[60:63], v[152:155], v[184:187], v[60:63]
	v_mfma_f32_16x16x32_bf16 v[56:59], v[160:163], v[184:187], v[56:59]
	v_mfma_f32_16x16x32_bf16 v[44:47], v[152:155], v[192:195], v[44:47]
	v_mfma_f32_16x16x32_bf16 v[40:43], v[160:163], v[192:195], v[40:43]
	v_mfma_f32_16x16x32_bf16 v[28:31], v[152:155], v[200:203], v[28:31]
	v_mfma_f32_16x16x32_bf16 v[24:27], v[160:163], v[200:203], v[24:27]
	v_mfma_f32_16x16x32_bf16 v[12:15], v[152:155], v[210:213], v[12:15]
	v_mfma_f32_16x16x32_bf16 v[8:11], v[160:163], v[210:213], v[8:11]
	v_mfma_f32_16x16x32_bf16 v[52:55], v[164:167], v[180:183], v[52:55]
	v_mfma_f32_16x16x32_bf16 v[48:51], v[172:175], v[180:183], v[48:51]
	v_mfma_f32_16x16x32_bf16 v[36:39], v[164:167], v[188:191], v[36:39]
	v_mfma_f32_16x16x32_bf16 v[32:35], v[172:175], v[188:191], v[32:35]
	v_mfma_f32_16x16x32_bf16 v[20:23], v[164:167], v[196:199], v[20:23]
	v_mfma_f32_16x16x32_bf16 v[16:19], v[172:175], v[196:199], v[16:19]
	v_mfma_f32_16x16x32_bf16 v[4:7], v[164:167], v[204:207], v[4:7]
	v_mfma_f32_16x16x32_bf16 v[0:3], v[172:175], v[204:207], v[0:3]
	v_mfma_f32_16x16x32_bf16 v[52:55], v[168:171], v[184:187], v[52:55]
	v_mfma_f32_16x16x32_bf16 v[48:51], v[176:179], v[184:187], v[48:51]
	v_mfma_f32_16x16x32_bf16 v[36:39], v[168:171], v[192:195], v[36:39]
	v_mfma_f32_16x16x32_bf16 v[32:35], v[176:179], v[192:195], v[32:35]
	v_mfma_f32_16x16x32_bf16 v[20:23], v[168:171], v[200:203], v[20:23]
	v_mfma_f32_16x16x32_bf16 v[16:19], v[176:179], v[200:203], v[16:19]
	v_mfma_f32_16x16x32_bf16 v[4:7], v[168:171], v[210:213], v[4:7]
	v_mfma_f32_16x16x32_bf16 v[0:3], v[176:179], v[210:213], v[0:3]
	s_barrier
	s_add_i32 s77, 0, 0x18000
	v_add_u32_e32 v151, s77, v145
	s_add_i32 s78, 0, 0x1c000
	ds_read_b128 v[140:143], v151
	ds_read_b128 v[152:155], v151 offset:1024
	ds_read_b128 v[156:159], v151 offset:2048
	ds_read_b128 v[160:163], v151 offset:3072
	v_add_u32_e32 v151, s78, v145
	ds_read_b128 v[164:167], v151
	ds_read_b128 v[168:171], v151 offset:1024
	ds_read_b128 v[172:175], v151 offset:2048
	ds_read_b128 v[176:179], v151 offset:3072
	s_add_u32 s58, s58, 0x80000
	s_addc_u32 s59, s59, 0
	s_mov_b32 m0, s62
	v_lshl_add_u64 v[222:223], s[58:59], 0, v[128:129]
	ds_read_b128 v[180:183], v149 offset:32768
	ds_read_b128 v[184:187], v149 offset:33792
	ds_read_b128 v[188:191], v149 offset:34816
	ds_read_b128 v[192:195], v149 offset:35840
	ds_read_b128 v[196:199], v149 offset:36864
	ds_read_b128 v[200:203], v149 offset:37888
	ds_read_b128 v[204:207], v149 offset:38912
	ds_read_b128 v[210:213], v149 offset:39936
	global_load_lds_dwordx4 v[222:223], off
	v_lshl_add_u64 v[222:223], s[58:59], 0, v[130:131]
	s_mov_b32 m0, s63
	s_nop 0
	global_load_lds_dwordx4 v[222:223], off
	s_waitcnt vmcnt(8)
	s_waitcnt lgkmcnt(0)
	s_barrier
	s_waitcnt lgkmcnt(0)
	v_mfma_f32_16x16x32_bf16 v[124:127], v[140:143], v[180:183], v[124:127]
	v_mfma_f32_16x16x32_bf16 v[120:123], v[156:159], v[180:183], v[120:123]
	v_mfma_f32_16x16x32_bf16 v[108:111], v[140:143], v[188:191], v[108:111]
	v_mfma_f32_16x16x32_bf16 v[104:107], v[156:159], v[188:191], v[104:107]
	v_mfma_f32_16x16x32_bf16 v[92:95], v[140:143], v[196:199], v[92:95]
	v_mfma_f32_16x16x32_bf16 v[88:91], v[156:159], v[196:199], v[88:91]
	v_mfma_f32_16x16x32_bf16 v[76:79], v[140:143], v[204:207], v[76:79]
	v_mfma_f32_16x16x32_bf16 v[72:75], v[156:159], v[204:207], v[72:75]
	v_mfma_f32_16x16x32_bf16 v[124:127], v[152:155], v[184:187], v[124:127]
	v_mfma_f32_16x16x32_bf16 v[120:123], v[160:163], v[184:187], v[120:123]
	v_mfma_f32_16x16x32_bf16 v[108:111], v[152:155], v[192:195], v[108:111]
	v_mfma_f32_16x16x32_bf16 v[104:107], v[160:163], v[192:195], v[104:107]
	v_mfma_f32_16x16x32_bf16 v[92:95], v[152:155], v[200:203], v[92:95]
	v_mfma_f32_16x16x32_bf16 v[88:91], v[160:163], v[200:203], v[88:91]
	v_mfma_f32_16x16x32_bf16 v[76:79], v[152:155], v[210:213], v[76:79]
	v_mfma_f32_16x16x32_bf16 v[72:75], v[160:163], v[210:213], v[72:75]
	v_mfma_f32_16x16x32_bf16 v[116:119], v[164:167], v[180:183], v[116:119]
	v_mfma_f32_16x16x32_bf16 v[112:115], v[172:175], v[180:183], v[112:115]
	v_mfma_f32_16x16x32_bf16 v[100:103], v[164:167], v[188:191], v[100:103]
	v_mfma_f32_16x16x32_bf16 v[96:99], v[172:175], v[188:191], v[96:99]
	v_mfma_f32_16x16x32_bf16 v[84:87], v[164:167], v[196:199], v[84:87]
	v_mfma_f32_16x16x32_bf16 v[80:83], v[172:175], v[196:199], v[80:83]
	v_mfma_f32_16x16x32_bf16 v[68:71], v[164:167], v[204:207], v[68:71]
	v_mfma_f32_16x16x32_bf16 v[64:67], v[172:175], v[204:207], v[64:67]
	v_mfma_f32_16x16x32_bf16 v[116:119], v[168:171], v[184:187], v[116:119]
	v_mfma_f32_16x16x32_bf16 v[112:115], v[176:179], v[184:187], v[112:115]
	v_mfma_f32_16x16x32_bf16 v[100:103], v[168:171], v[192:195], v[100:103]
	v_mfma_f32_16x16x32_bf16 v[96:99], v[176:179], v[192:195], v[96:99]
	v_mfma_f32_16x16x32_bf16 v[84:87], v[168:171], v[200:203], v[84:87]
	v_mfma_f32_16x16x32_bf16 v[80:83], v[176:179], v[200:203], v[80:83]
	v_mfma_f32_16x16x32_bf16 v[68:71], v[168:171], v[210:213], v[68:71]
	v_mfma_f32_16x16x32_bf16 v[64:67], v[176:179], v[210:213], v[64:67]
	s_barrier
	s_add_i32 s58, s77, s3
	v_lshl_add_u64 v[214:215], v[214:215], 0, s[38:39]
	s_mov_b32 m0, s58
	ds_read_b128 v[180:183], v149 offset:49152
	ds_read_b128 v[184:187], v149 offset:50176
	ds_read_b128 v[188:191], v149 offset:51200
	ds_read_b128 v[192:195], v149 offset:52224
	ds_read_b128 v[196:199], v149 offset:53248
	ds_read_b128 v[200:203], v149 offset:54272
	ds_read_b128 v[204:207], v149 offset:55296
	ds_read_b128 v[210:213], v149 offset:56320
	global_load_lds_dwordx4 v[214:215], off
	s_add_i32 m0, s58, 0x2000
	s_add_u32 s56, s56, 0x80080
	v_lshl_add_u64 v[214:215], v[216:217], 0, s[38:39]
	s_addc_u32 s57, s57, 0
	s_add_i32 s58, s78, s3
	global_load_lds_dwordx4 v[214:215], off
	v_lshl_add_u64 v[214:215], s[56:57], 0, v[128:129]
	s_mov_b32 m0, s58
	s_nop 0
	global_load_lds_dwordx4 v[214:215], off
	v_lshl_add_u64 v[214:215], s[56:57], 0, v[130:131]
	s_add_i32 m0, s58, 0x2000
	s_nop 0
	global_load_lds_dwordx4 v[214:215], off
	v_lshl_add_u64 v[214:215], v[218:219], 0, s[38:39]
	s_mov_b32 m0, s65
	s_nop 0
	global_load_lds_dwordx4 v[214:215], off
	v_lshl_add_u64 v[214:215], v[220:221], 0, s[38:39]
	s_mov_b32 m0, s66
	s_nop 0
	global_load_lds_dwordx4 v[214:215], off
	s_waitcnt vmcnt(8)
	s_waitcnt lgkmcnt(0)
	s_barrier
	s_waitcnt lgkmcnt(0)
	v_mfma_f32_16x16x32_bf16 v[60:63], v[140:143], v[180:183], v[60:63]
	v_mfma_f32_16x16x32_bf16 v[56:59], v[156:159], v[180:183], v[56:59]
	v_mfma_f32_16x16x32_bf16 v[44:47], v[140:143], v[188:191], v[44:47]
	v_mfma_f32_16x16x32_bf16 v[40:43], v[156:159], v[188:191], v[40:43]
	v_mfma_f32_16x16x32_bf16 v[28:31], v[140:143], v[196:199], v[28:31]
	v_mfma_f32_16x16x32_bf16 v[24:27], v[156:159], v[196:199], v[24:27]
	v_mfma_f32_16x16x32_bf16 v[12:15], v[140:143], v[204:207], v[12:15]
	v_mfma_f32_16x16x32_bf16 v[8:11], v[156:159], v[204:207], v[8:11]
	v_mfma_f32_16x16x32_bf16 v[60:63], v[152:155], v[184:187], v[60:63]
	v_mfma_f32_16x16x32_bf16 v[56:59], v[160:163], v[184:187], v[56:59]
	v_mfma_f32_16x16x32_bf16 v[44:47], v[152:155], v[192:195], v[44:47]
	v_mfma_f32_16x16x32_bf16 v[40:43], v[160:163], v[192:195], v[40:43]
	v_mfma_f32_16x16x32_bf16 v[28:31], v[152:155], v[200:203], v[28:31]
	v_mfma_f32_16x16x32_bf16 v[24:27], v[160:163], v[200:203], v[24:27]
	v_mfma_f32_16x16x32_bf16 v[12:15], v[152:155], v[210:213], v[12:15]
	v_mfma_f32_16x16x32_bf16 v[8:11], v[160:163], v[210:213], v[8:11]
	v_mfma_f32_16x16x32_bf16 v[52:55], v[164:167], v[180:183], v[52:55]
	v_mfma_f32_16x16x32_bf16 v[48:51], v[172:175], v[180:183], v[48:51]
	v_mfma_f32_16x16x32_bf16 v[36:39], v[164:167], v[188:191], v[36:39]
	v_mfma_f32_16x16x32_bf16 v[32:35], v[172:175], v[188:191], v[32:35]
	v_mfma_f32_16x16x32_bf16 v[20:23], v[164:167], v[196:199], v[20:23]
	v_mfma_f32_16x16x32_bf16 v[16:19], v[172:175], v[196:199], v[16:19]
	v_mfma_f32_16x16x32_bf16 v[4:7], v[164:167], v[204:207], v[4:7]
	v_mfma_f32_16x16x32_bf16 v[0:3], v[172:175], v[204:207], v[0:3]
	v_mfma_f32_16x16x32_bf16 v[52:55], v[168:171], v[184:187], v[52:55]
	v_mfma_f32_16x16x32_bf16 v[48:51], v[176:179], v[184:187], v[48:51]
	v_mfma_f32_16x16x32_bf16 v[36:39], v[168:171], v[192:195], v[36:39]
	v_mfma_f32_16x16x32_bf16 v[32:35], v[176:179], v[192:195], v[32:35]
	v_mfma_f32_16x16x32_bf16 v[20:23], v[168:171], v[200:203], v[20:23]
	v_mfma_f32_16x16x32_bf16 v[16:19], v[176:179], v[200:203], v[16:19]
	v_mfma_f32_16x16x32_bf16 v[4:7], v[168:171], v[210:213], v[4:7]
	v_mfma_f32_16x16x32_bf16 v[0:3], v[176:179], v[210:213], v[0:3]
	s_barrier
	s_add_i32 s76, s76, 2
	s_add_u32 s54, s54, 0x100
	s_addc_u32 s55, s55, 0
	s_add_u32 s74, s74, 0x100
	s_addc_u32 s75, s75, 0
	s_cmp_gt_u32 s76, 29
	s_cbranch_scc0 .LBB0_545
	s_and_b64 vcc, exec, s[40:41]
	s_cbranch_vccz .LBB0_548
	s_barrier

.LBB0_639:
	ds_read_b128 v[144:147], v152
	ds_read_b128 v[156:159], v152 offset:1024
	ds_read_b128 v[160:163], v152 offset:2048
	ds_read_b128 v[164:167], v152 offset:3072
	ds_read_b128 v[168:171], v153
	ds_read_b128 v[172:175], v153 offset:1024
	ds_read_b128 v[176:179], v153 offset:2048
	ds_read_b128 v[180:183], v153 offset:3072
	s_add_u32 s46, s44, 0xfff80080
	s_addc_u32 s47, s45, -1
	s_cmp_eq_u32 s71, 28
	s_cselect_b32 s49, s37, s47
	s_cselect_b32 s48, s67, s46
	s_cselect_b32 s47, s21, s70
	s_cselect_b32 s46, s68, s69
	v_lshl_add_u64 v[218:219], s[44:45], 0, v[136:137]
	s_add_i32 m0, s43, 0xc000
	ds_read_b128 v[184:187], v154
	ds_read_b128 v[188:191], v154 offset:1024
	ds_read_b128 v[192:195], v154 offset:2048
	ds_read_b128 v[196:199], v154 offset:3072
	ds_read_b128 v[200:203], v154 offset:4096
	ds_read_b128 v[204:207], v154 offset:5120
	ds_read_b128 v[210:213], v154 offset:6144
	ds_read_b128 v[214:217], v154 offset:7168
	global_load_lds_dwordx4 v[218:219], off
	v_lshl_add_u64 v[218:219], s[44:45], 0, v[138:139]
	s_add_i32 m0, s43, 0xe000
	s_nop 0
	global_load_lds_dwordx4 v[218:219], off
	s_waitcnt vmcnt(8)
	s_waitcnt lgkmcnt(0)
	s_barrier
	s_waitcnt lgkmcnt(0)
	v_mfma_f32_16x16x32_bf16 v[124:127], v[144:147], v[184:187], v[124:127]
	v_mfma_f32_16x16x32_bf16 v[120:123], v[160:163], v[184:187], v[120:123]
	v_mfma_f32_16x16x32_bf16 v[108:111], v[144:147], v[192:195], v[108:111]
	v_mfma_f32_16x16x32_bf16 v[104:107], v[160:163], v[192:195], v[104:107]
	v_mfma_f32_16x16x32_bf16 v[92:95], v[144:147], v[200:203], v[92:95]
	v_mfma_f32_16x16x32_bf16 v[88:91], v[160:163], v[200:203], v[88:91]
	v_mfma_f32_16x16x32_bf16 v[76:79], v[144:147], v[210:213], v[76:79]
	v_mfma_f32_16x16x32_bf16 v[72:75], v[160:163], v[210:213], v[72:75]
	v_mfma_f32_16x16x32_bf16 v[124:127], v[156:159], v[188:191], v[124:127]
	v_mfma_f32_16x16x32_bf16 v[120:123], v[164:167], v[188:191], v[120:123]
	v_mfma_f32_16x16x32_bf16 v[108:111], v[156:159], v[196:199], v[108:111]
	v_mfma_f32_16x16x32_bf16 v[104:107], v[164:167], v[196:199], v[104:107]
	v_mfma_f32_16x16x32_bf16 v[92:95], v[156:159], v[204:207], v[92:95]
	v_mfma_f32_16x16x32_bf16 v[88:91], v[164:167], v[204:207], v[88:91]
	v_mfma_f32_16x16x32_bf16 v[76:79], v[156:159], v[214:217], v[76:79]
	v_mfma_f32_16x16x32_bf16 v[72:75], v[164:167], v[214:217], v[72:75]
	v_mfma_f32_16x16x32_bf16 v[116:119], v[168:171], v[184:187], v[116:119]
	v_mfma_f32_16x16x32_bf16 v[112:115], v[176:179], v[184:187], v[112:115]
	v_mfma_f32_16x16x32_bf16 v[100:103], v[168:171], v[192:195], v[100:103]
	v_mfma_f32_16x16x32_bf16 v[96:99], v[176:179], v[192:195], v[96:99]
	v_mfma_f32_16x16x32_bf16 v[84:87], v[168:171], v[200:203], v[84:87]
	v_mfma_f32_16x16x32_bf16 v[80:83], v[176:179], v[200:203], v[80:83]
	v_mfma_f32_16x16x32_bf16 v[68:71], v[168:171], v[210:213], v[68:71]
	v_mfma_f32_16x16x32_bf16 v[64:67], v[176:179], v[210:213], v[64:67]
	v_mfma_f32_16x16x32_bf16 v[116:119], v[172:175], v[188:191], v[116:119]
	v_mfma_f32_16x16x32_bf16 v[112:115], v[180:183], v[188:191], v[112:115]
	v_mfma_f32_16x16x32_bf16 v[100:103], v[172:175], v[196:199], v[100:103]
	v_mfma_f32_16x16x32_bf16 v[96:99], v[180:183], v[196:199], v[96:99]
	v_mfma_f32_16x16x32_bf16 v[84:87], v[172:175], v[204:207], v[84:87]
	v_mfma_f32_16x16x32_bf16 v[80:83], v[180:183], v[204:207], v[80:83]
	v_mfma_f32_16x16x32_bf16 v[68:71], v[172:175], v[214:217], v[68:71]
	v_mfma_f32_16x16x32_bf16 v[64:67], v[180:183], v[214:217], v[64:67]
	s_barrier
	s_add_i32 s72, s60, s51
	v_lshl_add_u64 v[218:219], s[46:47], 0, v[132:133]
	s_mov_b32 m0, s72
	ds_read_b128 v[184:187], v154 offset:16384
	ds_read_b128 v[188:191], v154 offset:17408
	ds_read_b128 v[192:195], v154 offset:18432
	ds_read_b128 v[196:199], v154 offset:19456
	ds_read_b128 v[200:203], v154 offset:20480
	ds_read_b128 v[204:207], v154 offset:21504
	ds_read_b128 v[210:213], v154 offset:22528
	ds_read_b128 v[214:217], v154 offset:23552
	global_load_lds_dwordx4 v[218:219], off
	s_add_i32 m0, s72, 0x2000
	s_add_u32 s72, s46, 0x80000
	v_lshl_add_u64 v[220:221], s[46:47], 0, v[128:129]
	s_addc_u32 s73, s47, 0
	s_add_i32 s74, s61, s51
	global_load_lds_dwordx4 v[220:221], off
	v_lshl_add_u64 v[222:223], s[72:73], 0, v[132:133]
	s_mov_b32 m0, s74
	v_lshl_add_u64 v[224:225], s[48:49], 0, v[130:131]
	global_load_lds_dwordx4 v[222:223], off
	v_lshl_add_u64 v[222:223], s[72:73], 0, v[128:129]
	s_add_i32 m0, s74, 0x2000
	s_nop 0
	global_load_lds_dwordx4 v[222:223], off
	v_lshl_add_u64 v[222:223], s[48:49], 0, v[134:135]
	s_mov_b32 m0, s43
	s_nop 0
	global_load_lds_dwordx4 v[222:223], off
	s_mov_b32 m0, s55
	s_nop 0
	global_load_lds_dwordx4 v[224:225], off
	s_waitcnt vmcnt(8)
	s_waitcnt lgkmcnt(0)
	s_barrier
	s_waitcnt lgkmcnt(0)
	v_mfma_f32_16x16x32_bf16 v[60:63], v[144:147], v[184:187], v[60:63]
	v_mfma_f32_16x16x32_bf16 v[56:59], v[160:163], v[184:187], v[56:59]
	v_mfma_f32_16x16x32_bf16 v[44:47], v[144:147], v[192:195], v[44:47]
	v_mfma_f32_16x16x32_bf16 v[40:43], v[160:163], v[192:195], v[40:43]
	v_mfma_f32_16x16x32_bf16 v[28:31], v[144:147], v[200:203], v[28:31]
	v_mfma_f32_16x16x32_bf16 v[24:27], v[160:163], v[200:203], v[24:27]
	v_mfma_f32_16x16x32_bf16 v[12:15], v[144:147], v[210:213], v[12:15]
	v_mfma_f32_16x16x32_bf16 v[8:11], v[160:163], v[210:213], v[8:11]
	v_mfma_f32_16x16x32_bf16 v[60:63], v[156:159], v[188:191], v[60:63]
	v_mfma_f32_16x16x32_bf16 v[56:59], v[164:167], v[188:191], v[56:59]
	v_mfma_f32_16x16x32_bf16 v[44:47], v[156:159], v[196:199], v[44:47]
	v_mfma_f32_16x16x32_bf16 v[40:43], v[164:167], v[196:199], v[40:43]
	v_mfma_f32_16x16x32_bf16 v[28:31], v[156:159], v[204:207], v[28:31]
	v_mfma_f32_16x16x32_bf16 v[24:27], v[164:167], v[204:207], v[24:27]
	v_mfma_f32_16x16x32_bf16 v[12:15], v[156:159], v[214:217], v[12:15]
	v_mfma_f32_16x16x32_bf16 v[8:11], v[164:167], v[214:217], v[8:11]
	v_mfma_f32_16x16x32_bf16 v[52:55], v[168:171], v[184:187], v[52:55]
	v_mfma_f32_16x16x32_bf16 v[48:51], v[176:179], v[184:187], v[48:51]
	v_mfma_f32_16x16x32_bf16 v[36:39], v[168:171], v[192:195], v[36:39]
	v_mfma_f32_16x16x32_bf16 v[32:35], v[176:179], v[192:195], v[32:35]
	v_mfma_f32_16x16x32_bf16 v[20:23], v[168:171], v[200:203], v[20:23]
	v_mfma_f32_16x16x32_bf16 v[16:19], v[176:179], v[200:203], v[16:19]
	v_mfma_f32_16x16x32_bf16 v[4:7], v[168:171], v[210:213], v[4:7]
	v_mfma_f32_16x16x32_bf16 v[0:3], v[176:179], v[210:213], v[0:3]
	v_mfma_f32_16x16x32_bf16 v[52:55], v[172:175], v[188:191], v[52:55]
	v_mfma_f32_16x16x32_bf16 v[48:51], v[180:183], v[188:191], v[48:51]
	v_mfma_f32_16x16x32_bf16 v[36:39], v[172:175], v[196:199], v[36:39]
	v_mfma_f32_16x16x32_bf16 v[32:35], v[180:183], v[196:199], v[32:35]
	v_mfma_f32_16x16x32_bf16 v[20:23], v[172:175], v[204:207], v[20:23]
	v_mfma_f32_16x16x32_bf16 v[16:19], v[180:183], v[204:207], v[16:19]
	v_mfma_f32_16x16x32_bf16 v[4:7], v[172:175], v[214:217], v[4:7]
	v_mfma_f32_16x16x32_bf16 v[0:3], v[180:183], v[214:217], v[0:3]
	s_barrier
	s_add_i32 s72, 0, 0x18000
	v_add_u32_e32 v155, s72, v149
	s_add_i32 s73, 0, 0x1c000
	ds_read_b128 v[144:147], v155
	ds_read_b128 v[156:159], v155 offset:1024
	ds_read_b128 v[160:163], v155 offset:2048
	ds_read_b128 v[164:167], v155 offset:3072
	v_add_u32_e32 v155, s73, v149
	ds_read_b128 v[168:171], v155
	ds_read_b128 v[172:175], v155 offset:1024
	ds_read_b128 v[176:179], v155 offset:2048
	ds_read_b128 v[180:183], v155 offset:3072
	s_add_u32 s48, s48, 0x80000
	s_addc_u32 s49, s49, 0
	s_mov_b32 m0, s56
	v_lshl_add_u64 v[226:227], s[48:49], 0, v[134:135]
	ds_read_b128 v[184:187], v154 offset:32768
	ds_read_b128 v[188:191], v154 offset:33792
	ds_read_b128 v[192:195], v154 offset:34816
	ds_read_b128 v[196:199], v154 offset:35840
	ds_read_b128 v[200:203], v154 offset:36864
	ds_read_b128 v[204:207], v154 offset:37888
	ds_read_b128 v[210:213], v154 offset:38912
	ds_read_b128 v[214:217], v154 offset:39936
	global_load_lds_dwordx4 v[226:227], off
	v_lshl_add_u64 v[226:227], s[48:49], 0, v[130:131]
	s_mov_b32 m0, s57
	s_nop 0
	global_load_lds_dwordx4 v[226:227], off
	s_waitcnt vmcnt(8)
	s_waitcnt lgkmcnt(0)
	s_barrier
	s_waitcnt lgkmcnt(0)
	v_mfma_f32_16x16x32_bf16 v[124:127], v[144:147], v[184:187], v[124:127]
	v_mfma_f32_16x16x32_bf16 v[120:123], v[160:163], v[184:187], v[120:123]
	v_mfma_f32_16x16x32_bf16 v[108:111], v[144:147], v[192:195], v[108:111]
	v_mfma_f32_16x16x32_bf16 v[104:107], v[160:163], v[192:195], v[104:107]
	v_mfma_f32_16x16x32_bf16 v[92:95], v[144:147], v[200:203], v[92:95]
	v_mfma_f32_16x16x32_bf16 v[88:91], v[160:163], v[200:203], v[88:91]
	v_mfma_f32_16x16x32_bf16 v[76:79], v[144:147], v[210:213], v[76:79]
	v_mfma_f32_16x16x32_bf16 v[72:75], v[160:163], v[210:213], v[72:75]
	v_mfma_f32_16x16x32_bf16 v[124:127], v[156:159], v[188:191], v[124:127]
	v_mfma_f32_16x16x32_bf16 v[120:123], v[164:167], v[188:191], v[120:123]
	v_mfma_f32_16x16x32_bf16 v[108:111], v[156:159], v[196:199], v[108:111]
	v_mfma_f32_16x16x32_bf16 v[104:107], v[164:167], v[196:199], v[104:107]
	v_mfma_f32_16x16x32_bf16 v[92:95], v[156:159], v[204:207], v[92:95]
	v_mfma_f32_16x16x32_bf16 v[88:91], v[164:167], v[204:207], v[88:91]
	v_mfma_f32_16x16x32_bf16 v[76:79], v[156:159], v[214:217], v[76:79]
	v_mfma_f32_16x16x32_bf16 v[72:75], v[164:167], v[214:217], v[72:75]
	v_mfma_f32_16x16x32_bf16 v[116:119], v[168:171], v[184:187], v[116:119]
	v_mfma_f32_16x16x32_bf16 v[112:115], v[176:179], v[184:187], v[112:115]
	v_mfma_f32_16x16x32_bf16 v[100:103], v[168:171], v[192:195], v[100:103]
	v_mfma_f32_16x16x32_bf16 v[96:99], v[176:179], v[192:195], v[96:99]
	v_mfma_f32_16x16x32_bf16 v[84:87], v[168:171], v[200:203], v[84:87]
	v_mfma_f32_16x16x32_bf16 v[80:83], v[176:179], v[200:203], v[80:83]
	v_mfma_f32_16x16x32_bf16 v[68:71], v[168:171], v[210:213], v[68:71]
	v_mfma_f32_16x16x32_bf16 v[64:67], v[176:179], v[210:213], v[64:67]
	v_mfma_f32_16x16x32_bf16 v[116:119], v[172:175], v[188:191], v[116:119]
	v_mfma_f32_16x16x32_bf16 v[112:115], v[180:183], v[188:191], v[112:115]
	v_mfma_f32_16x16x32_bf16 v[100:103], v[172:175], v[196:199], v[100:103]
	v_mfma_f32_16x16x32_bf16 v[96:99], v[180:183], v[196:199], v[96:99]
	v_mfma_f32_16x16x32_bf16 v[84:87], v[172:175], v[204:207], v[84:87]
	v_mfma_f32_16x16x32_bf16 v[80:83], v[180:183], v[204:207], v[80:83]
	v_mfma_f32_16x16x32_bf16 v[68:71], v[172:175], v[214:217], v[68:71]
	v_mfma_f32_16x16x32_bf16 v[64:67], v[180:183], v[214:217], v[64:67]
	s_barrier
	s_add_i32 s48, s72, s51
	v_lshl_add_u64 v[218:219], v[218:219], 0, s[6:7]
	s_mov_b32 m0, s48
	ds_read_b128 v[184:187], v154 offset:49152
	ds_read_b128 v[188:191], v154 offset:50176
	ds_read_b128 v[192:195], v154 offset:51200
	ds_read_b128 v[196:199], v154 offset:52224
	ds_read_b128 v[200:203], v154 offset:53248
	ds_read_b128 v[204:207], v154 offset:54272
	ds_read_b128 v[210:213], v154 offset:55296
	ds_read_b128 v[214:217], v154 offset:56320
	global_load_lds_dwordx4 v[218:219], off
	s_add_i32 m0, s48, 0x2000
	s_add_u32 s46, s46, 0x80080
	v_lshl_add_u64 v[218:219], v[220:221], 0, s[6:7]
	s_addc_u32 s47, s47, 0
	s_add_i32 s48, s73, s51
	global_load_lds_dwordx4 v[218:219], off
	v_lshl_add_u64 v[218:219], s[46:47], 0, v[132:133]
	s_mov_b32 m0, s48
	s_nop 0
	global_load_lds_dwordx4 v[218:219], off
	v_lshl_add_u64 v[218:219], s[46:47], 0, v[128:129]
	s_add_i32 m0, s48, 0x2000
	s_nop 0
	global_load_lds_dwordx4 v[218:219], off
	v_lshl_add_u64 v[218:219], v[222:223], 0, s[6:7]
	s_mov_b32 m0, s58
	s_nop 0
	global_load_lds_dwordx4 v[218:219], off
	v_lshl_add_u64 v[218:219], v[224:225], 0, s[6:7]
	s_mov_b32 m0, s59
	s_nop 0
	global_load_lds_dwordx4 v[218:219], off
	s_waitcnt vmcnt(8)
	s_waitcnt lgkmcnt(0)
	s_barrier
	s_waitcnt lgkmcnt(0)
	v_mfma_f32_16x16x32_bf16 v[60:63], v[144:147], v[184:187], v[60:63]
	v_mfma_f32_16x16x32_bf16 v[56:59], v[160:163], v[184:187], v[56:59]
	v_mfma_f32_16x16x32_bf16 v[44:47], v[144:147], v[192:195], v[44:47]
	v_mfma_f32_16x16x32_bf16 v[40:43], v[160:163], v[192:195], v[40:43]
	v_mfma_f32_16x16x32_bf16 v[28:31], v[144:147], v[200:203], v[28:31]
	v_mfma_f32_16x16x32_bf16 v[24:27], v[160:163], v[200:203], v[24:27]
	v_mfma_f32_16x16x32_bf16 v[12:15], v[144:147], v[210:213], v[12:15]
	v_mfma_f32_16x16x32_bf16 v[8:11], v[160:163], v[210:213], v[8:11]
	v_mfma_f32_16x16x32_bf16 v[60:63], v[156:159], v[188:191], v[60:63]
	v_mfma_f32_16x16x32_bf16 v[56:59], v[164:167], v[188:191], v[56:59]
	v_mfma_f32_16x16x32_bf16 v[44:47], v[156:159], v[196:199], v[44:47]
	v_mfma_f32_16x16x32_bf16 v[40:43], v[164:167], v[196:199], v[40:43]
	v_mfma_f32_16x16x32_bf16 v[28:31], v[156:159], v[204:207], v[28:31]
	v_mfma_f32_16x16x32_bf16 v[24:27], v[164:167], v[204:207], v[24:27]
	v_mfma_f32_16x16x32_bf16 v[12:15], v[156:159], v[214:217], v[12:15]
	v_mfma_f32_16x16x32_bf16 v[8:11], v[164:167], v[214:217], v[8:11]
	v_mfma_f32_16x16x32_bf16 v[52:55], v[168:171], v[184:187], v[52:55]
	v_mfma_f32_16x16x32_bf16 v[48:51], v[176:179], v[184:187], v[48:51]
	v_mfma_f32_16x16x32_bf16 v[36:39], v[168:171], v[192:195], v[36:39]
	v_mfma_f32_16x16x32_bf16 v[32:35], v[176:179], v[192:195], v[32:35]
	v_mfma_f32_16x16x32_bf16 v[20:23], v[168:171], v[200:203], v[20:23]
	v_mfma_f32_16x16x32_bf16 v[16:19], v[176:179], v[200:203], v[16:19]
	v_mfma_f32_16x16x32_bf16 v[4:7], v[168:171], v[210:213], v[4:7]
	v_mfma_f32_16x16x32_bf16 v[0:3], v[176:179], v[210:213], v[0:3]
	v_mfma_f32_16x16x32_bf16 v[52:55], v[172:175], v[188:191], v[52:55]
	v_mfma_f32_16x16x32_bf16 v[48:51], v[180:183], v[188:191], v[48:51]
	v_mfma_f32_16x16x32_bf16 v[36:39], v[172:175], v[196:199], v[36:39]
	v_mfma_f32_16x16x32_bf16 v[32:35], v[180:183], v[196:199], v[32:35]
	v_mfma_f32_16x16x32_bf16 v[20:23], v[172:175], v[204:207], v[20:23]
	v_mfma_f32_16x16x32_bf16 v[16:19], v[180:183], v[204:207], v[16:19]
	v_mfma_f32_16x16x32_bf16 v[4:7], v[172:175], v[214:217], v[4:7]
	v_mfma_f32_16x16x32_bf16 v[0:3], v[180:183], v[214:217], v[0:3]
	s_barrier
	s_add_i32 s71, s71, 2
	s_add_u32 s44, s44, 0x100
	s_addc_u32 s45, s45, 0
	s_add_u32 s69, s69, 0x100
	s_addc_u32 s70, s70, 0
	s_cmp_gt_u32 s71, 29
	s_cbranch_scc0 .LBB0_639
	s_and_b64 vcc, exec, s[18:19]
	s_cbranch_vccz .LBB0_642
	s_barrier

.LBB0_727:
	ds_read_b128 v[140:143], v147
	ds_read_b128 v[150:153], v147 offset:1024
	ds_read_b128 v[154:157], v147 offset:2048
	ds_read_b128 v[158:161], v147 offset:3072
	ds_read_b128 v[162:165], v148
	ds_read_b128 v[166:169], v148 offset:1024
	ds_read_b128 v[170:173], v148 offset:2048
	ds_read_b128 v[174:177], v148 offset:3072
	s_add_u32 s28, s26, 0xffea0080
	s_addc_u32 s29, s27, -1
	s_cmpk_eq_i32 s51, 0x54
	s_cselect_b32 s35, s5, s29
	s_cselect_b32 s34, s4, s28
	s_cselect_b32 s29, s23, s50
	s_cselect_b32 s28, s22, s49
	v_lshl_add_u64 v[210:211], s[26:27], 0, v[132:133]
	s_add_i32 m0, s33, 0xc000
	ds_read_b128 v[178:181], v149
	ds_read_b128 v[182:185], v149 offset:1024
	ds_read_b128 v[186:189], v149 offset:2048
	ds_read_b128 v[190:193], v149 offset:3072
	ds_read_b128 v[194:197], v149 offset:4096
	ds_read_b128 v[198:201], v149 offset:5120
	ds_read_b128 v[202:205], v149 offset:6144
	ds_read_b128 v[206:209], v149 offset:7168
	global_load_lds_dwordx4 v[210:211], off
	v_lshl_add_u64 v[210:211], s[26:27], 0, v[134:135]
	s_add_i32 m0, s33, 0xe000
	s_nop 0
	global_load_lds_dwordx4 v[210:211], off
	s_waitcnt vmcnt(8)
	s_waitcnt lgkmcnt(0)
	s_barrier
	s_waitcnt lgkmcnt(0)
	v_mfma_f32_16x16x32_bf16 v[124:127], v[140:143], v[178:181], v[124:127]
	v_mfma_f32_16x16x32_bf16 v[120:123], v[154:157], v[178:181], v[120:123]
	v_mfma_f32_16x16x32_bf16 v[108:111], v[140:143], v[186:189], v[108:111]
	v_mfma_f32_16x16x32_bf16 v[104:107], v[154:157], v[186:189], v[104:107]
	v_mfma_f32_16x16x32_bf16 v[92:95], v[140:143], v[194:197], v[92:95]
	v_mfma_f32_16x16x32_bf16 v[88:91], v[154:157], v[194:197], v[88:91]
	v_mfma_f32_16x16x32_bf16 v[76:79], v[140:143], v[202:205], v[76:79]
	v_mfma_f32_16x16x32_bf16 v[72:75], v[154:157], v[202:205], v[72:75]
	v_mfma_f32_16x16x32_bf16 v[124:127], v[150:153], v[182:185], v[124:127]
	v_mfma_f32_16x16x32_bf16 v[120:123], v[158:161], v[182:185], v[120:123]
	v_mfma_f32_16x16x32_bf16 v[108:111], v[150:153], v[190:193], v[108:111]
	v_mfma_f32_16x16x32_bf16 v[104:107], v[158:161], v[190:193], v[104:107]
	v_mfma_f32_16x16x32_bf16 v[92:95], v[150:153], v[198:201], v[92:95]
	v_mfma_f32_16x16x32_bf16 v[88:91], v[158:161], v[198:201], v[88:91]
	v_mfma_f32_16x16x32_bf16 v[76:79], v[150:153], v[206:209], v[76:79]
	v_mfma_f32_16x16x32_bf16 v[72:75], v[158:161], v[206:209], v[72:75]
	v_mfma_f32_16x16x32_bf16 v[116:119], v[162:165], v[178:181], v[116:119]
	v_mfma_f32_16x16x32_bf16 v[112:115], v[170:173], v[178:181], v[112:115]
	v_mfma_f32_16x16x32_bf16 v[100:103], v[162:165], v[186:189], v[100:103]
	v_mfma_f32_16x16x32_bf16 v[96:99], v[170:173], v[186:189], v[96:99]
	v_mfma_f32_16x16x32_bf16 v[84:87], v[162:165], v[194:197], v[84:87]
	v_mfma_f32_16x16x32_bf16 v[80:83], v[170:173], v[194:197], v[80:83]
	v_mfma_f32_16x16x32_bf16 v[68:71], v[162:165], v[202:205], v[68:71]
	v_mfma_f32_16x16x32_bf16 v[64:67], v[170:173], v[202:205], v[64:67]
	v_mfma_f32_16x16x32_bf16 v[116:119], v[166:169], v[182:185], v[116:119]
	v_mfma_f32_16x16x32_bf16 v[112:115], v[174:177], v[182:185], v[112:115]
	v_mfma_f32_16x16x32_bf16 v[100:103], v[166:169], v[190:193], v[100:103]
	v_mfma_f32_16x16x32_bf16 v[96:99], v[174:177], v[190:193], v[96:99]
	v_mfma_f32_16x16x32_bf16 v[84:87], v[166:169], v[198:201], v[84:87]
	v_mfma_f32_16x16x32_bf16 v[80:83], v[174:177], v[198:201], v[80:83]
	v_mfma_f32_16x16x32_bf16 v[68:71], v[166:169], v[206:209], v[68:71]
	v_mfma_f32_16x16x32_bf16 v[64:67], v[174:177], v[206:209], v[64:67]
	s_barrier
	s_add_i32 s52, s43, s31
	v_lshl_add_u64 v[210:211], s[28:29], 0, v[128:129]
	s_mov_b32 m0, s52
	ds_read_b128 v[178:181], v149 offset:16384
	ds_read_b128 v[182:185], v149 offset:17408
	ds_read_b128 v[186:189], v149 offset:18432
	ds_read_b128 v[190:193], v149 offset:19456
	ds_read_b128 v[194:197], v149 offset:20480
	ds_read_b128 v[198:201], v149 offset:21504
	ds_read_b128 v[202:205], v149 offset:22528
	ds_read_b128 v[206:209], v149 offset:23552
	global_load_lds_dwordx4 v[210:211], off
	s_add_i32 m0, s52, 0x2000
	s_add_u32 s52, s28, 0x160000
	v_lshl_add_u64 v[212:213], s[28:29], 0, v[130:131]
	s_addc_u32 s53, s29, 0
	s_add_i32 s54, s44, s31
	global_load_lds_dwordx4 v[212:213], off
	v_lshl_add_u64 v[214:215], s[52:53], 0, v[128:129]
	s_mov_b32 m0, s54
	v_lshl_add_u64 v[216:217], s[34:35], 0, v[130:131]
	global_load_lds_dwordx4 v[214:215], off
	v_lshl_add_u64 v[214:215], s[52:53], 0, v[130:131]
	s_add_i32 m0, s54, 0x2000
	s_nop 0
	global_load_lds_dwordx4 v[214:215], off
	v_lshl_add_u64 v[214:215], s[34:35], 0, v[128:129]
	s_mov_b32 m0, s33
	s_nop 0
	global_load_lds_dwordx4 v[214:215], off
	s_mov_b32 m0, s36
	s_nop 0
	global_load_lds_dwordx4 v[216:217], off
	s_waitcnt vmcnt(8)
	s_waitcnt lgkmcnt(0)
	s_barrier
	s_waitcnt lgkmcnt(0)
	v_mfma_f32_16x16x32_bf16 v[60:63], v[140:143], v[178:181], v[60:63]
	v_mfma_f32_16x16x32_bf16 v[56:59], v[154:157], v[178:181], v[56:59]
	v_mfma_f32_16x16x32_bf16 v[44:47], v[140:143], v[186:189], v[44:47]
	v_mfma_f32_16x16x32_bf16 v[40:43], v[154:157], v[186:189], v[40:43]
	v_mfma_f32_16x16x32_bf16 v[28:31], v[140:143], v[194:197], v[28:31]
	v_mfma_f32_16x16x32_bf16 v[24:27], v[154:157], v[194:197], v[24:27]
	v_mfma_f32_16x16x32_bf16 v[12:15], v[140:143], v[202:205], v[12:15]
	v_mfma_f32_16x16x32_bf16 v[8:11], v[154:157], v[202:205], v[8:11]
	v_mfma_f32_16x16x32_bf16 v[60:63], v[150:153], v[182:185], v[60:63]
	v_mfma_f32_16x16x32_bf16 v[56:59], v[158:161], v[182:185], v[56:59]
	v_mfma_f32_16x16x32_bf16 v[44:47], v[150:153], v[190:193], v[44:47]
	v_mfma_f32_16x16x32_bf16 v[40:43], v[158:161], v[190:193], v[40:43]
	v_mfma_f32_16x16x32_bf16 v[28:31], v[150:153], v[198:201], v[28:31]
	v_mfma_f32_16x16x32_bf16 v[24:27], v[158:161], v[198:201], v[24:27]
	v_mfma_f32_16x16x32_bf16 v[12:15], v[150:153], v[206:209], v[12:15]
	v_mfma_f32_16x16x32_bf16 v[8:11], v[158:161], v[206:209], v[8:11]
	v_mfma_f32_16x16x32_bf16 v[52:55], v[162:165], v[178:181], v[52:55]
	v_mfma_f32_16x16x32_bf16 v[48:51], v[170:173], v[178:181], v[48:51]
	v_mfma_f32_16x16x32_bf16 v[36:39], v[162:165], v[186:189], v[36:39]
	v_mfma_f32_16x16x32_bf16 v[32:35], v[170:173], v[186:189], v[32:35]
	v_mfma_f32_16x16x32_bf16 v[20:23], v[162:165], v[194:197], v[20:23]
	v_mfma_f32_16x16x32_bf16 v[16:19], v[170:173], v[194:197], v[16:19]
	v_mfma_f32_16x16x32_bf16 v[4:7], v[162:165], v[202:205], v[4:7]
	v_mfma_f32_16x16x32_bf16 v[0:3], v[170:173], v[202:205], v[0:3]
	v_mfma_f32_16x16x32_bf16 v[52:55], v[166:169], v[182:185], v[52:55]
	v_mfma_f32_16x16x32_bf16 v[48:51], v[174:177], v[182:185], v[48:51]
	v_mfma_f32_16x16x32_bf16 v[36:39], v[166:169], v[190:193], v[36:39]
	v_mfma_f32_16x16x32_bf16 v[32:35], v[174:177], v[190:193], v[32:35]
	v_mfma_f32_16x16x32_bf16 v[20:23], v[166:169], v[198:201], v[20:23]
	v_mfma_f32_16x16x32_bf16 v[16:19], v[174:177], v[198:201], v[16:19]
	v_mfma_f32_16x16x32_bf16 v[4:7], v[166:169], v[206:209], v[4:7]
	v_mfma_f32_16x16x32_bf16 v[0:3], v[174:177], v[206:209], v[0:3]
	s_barrier
	s_add_i32 s52, 0, 0x18000
	s_add_i32 s53, 0, 0x1c000
	v_add_u32_e32 v158, s52, v145
	v_add_u32_e32 v174, s53, v145
	ds_read_b128 v[140:143], v158
	ds_read_b128 v[150:153], v158 offset:1024
	ds_read_b128 v[154:157], v158 offset:2048
	ds_read_b128 v[158:161], v158 offset:3072
	ds_read_b128 v[162:165], v174
	ds_read_b128 v[166:169], v174 offset:1024
	ds_read_b128 v[170:173], v174 offset:2048
	ds_read_b128 v[174:177], v174 offset:3072
	s_add_u32 s34, s34, 0x160000
	s_addc_u32 s35, s35, 0
	s_mov_b32 m0, s37
	v_lshl_add_u64 v[218:219], s[34:35], 0, v[128:129]
	ds_read_b128 v[178:181], v149 offset:32768
	ds_read_b128 v[182:185], v149 offset:33792
	ds_read_b128 v[186:189], v149 offset:34816
	ds_read_b128 v[190:193], v149 offset:35840
	ds_read_b128 v[194:197], v149 offset:36864
	ds_read_b128 v[198:201], v149 offset:37888
	ds_read_b128 v[202:205], v149 offset:38912
	ds_read_b128 v[206:209], v149 offset:39936
	global_load_lds_dwordx4 v[218:219], off
	v_lshl_add_u64 v[218:219], s[34:35], 0, v[130:131]
	s_mov_b32 m0, s38
	s_nop 0
	global_load_lds_dwordx4 v[218:219], off
	s_waitcnt vmcnt(8)
	s_waitcnt lgkmcnt(0)
	s_barrier
	s_waitcnt lgkmcnt(0)
	v_mfma_f32_16x16x32_bf16 v[124:127], v[140:143], v[178:181], v[124:127]
	v_mfma_f32_16x16x32_bf16 v[120:123], v[154:157], v[178:181], v[120:123]
	v_mfma_f32_16x16x32_bf16 v[108:111], v[140:143], v[186:189], v[108:111]
	v_mfma_f32_16x16x32_bf16 v[104:107], v[154:157], v[186:189], v[104:107]
	v_mfma_f32_16x16x32_bf16 v[92:95], v[140:143], v[194:197], v[92:95]
	v_mfma_f32_16x16x32_bf16 v[88:91], v[154:157], v[194:197], v[88:91]
	v_mfma_f32_16x16x32_bf16 v[76:79], v[140:143], v[202:205], v[76:79]
	v_mfma_f32_16x16x32_bf16 v[72:75], v[154:157], v[202:205], v[72:75]
	v_mfma_f32_16x16x32_bf16 v[124:127], v[150:153], v[182:185], v[124:127]
	v_mfma_f32_16x16x32_bf16 v[120:123], v[158:161], v[182:185], v[120:123]
	v_mfma_f32_16x16x32_bf16 v[108:111], v[150:153], v[190:193], v[108:111]
	v_mfma_f32_16x16x32_bf16 v[104:107], v[158:161], v[190:193], v[104:107]
	v_mfma_f32_16x16x32_bf16 v[92:95], v[150:153], v[198:201], v[92:95]
	v_mfma_f32_16x16x32_bf16 v[88:91], v[158:161], v[198:201], v[88:91]
	v_mfma_f32_16x16x32_bf16 v[76:79], v[150:153], v[206:209], v[76:79]
	v_mfma_f32_16x16x32_bf16 v[72:75], v[158:161], v[206:209], v[72:75]
	v_mfma_f32_16x16x32_bf16 v[116:119], v[162:165], v[178:181], v[116:119]
	v_mfma_f32_16x16x32_bf16 v[112:115], v[170:173], v[178:181], v[112:115]
	v_mfma_f32_16x16x32_bf16 v[100:103], v[162:165], v[186:189], v[100:103]
	v_mfma_f32_16x16x32_bf16 v[96:99], v[170:173], v[186:189], v[96:99]
	v_mfma_f32_16x16x32_bf16 v[84:87], v[162:165], v[194:197], v[84:87]
	v_mfma_f32_16x16x32_bf16 v[80:83], v[170:173], v[194:197], v[80:83]
	v_mfma_f32_16x16x32_bf16 v[68:71], v[162:165], v[202:205], v[68:71]
	v_mfma_f32_16x16x32_bf16 v[64:67], v[170:173], v[202:205], v[64:67]
	v_mfma_f32_16x16x32_bf16 v[116:119], v[166:169], v[182:185], v[116:119]
	v_mfma_f32_16x16x32_bf16 v[112:115], v[174:177], v[182:185], v[112:115]
	v_mfma_f32_16x16x32_bf16 v[100:103], v[166:169], v[190:193], v[100:103]
	v_mfma_f32_16x16x32_bf16 v[96:99], v[174:177], v[190:193], v[96:99]
	v_mfma_f32_16x16x32_bf16 v[84:87], v[166:169], v[198:201], v[84:87]
	v_mfma_f32_16x16x32_bf16 v[80:83], v[174:177], v[198:201], v[80:83]
	v_mfma_f32_16x16x32_bf16 v[68:71], v[166:169], v[206:209], v[68:71]
	v_mfma_f32_16x16x32_bf16 v[64:67], v[174:177], v[206:209], v[64:67]
	s_barrier
	s_add_i32 s34, s52, s31
	v_lshl_add_u64 v[210:211], v[210:211], 0, s[18:19]
	s_mov_b32 m0, s34
	ds_read_b128 v[178:181], v149 offset:49152
	ds_read_b128 v[182:185], v149 offset:50176
	ds_read_b128 v[186:189], v149 offset:51200
	ds_read_b128 v[190:193], v149 offset:52224
	ds_read_b128 v[194:197], v149 offset:53248
	ds_read_b128 v[198:201], v149 offset:54272
	ds_read_b128 v[202:205], v149 offset:55296
	ds_read_b128 v[206:209], v149 offset:56320
	global_load_lds_dwordx4 v[210:211], off
	s_add_i32 m0, s34, 0x2000
	s_add_u32 s28, s28, 0x160080
	v_lshl_add_u64 v[210:211], v[212:213], 0, s[18:19]
	s_addc_u32 s29, s29, 0
	s_add_i32 s34, s53, s31
	global_load_lds_dwordx4 v[210:211], off
	v_lshl_add_u64 v[210:211], s[28:29], 0, v[128:129]
	s_mov_b32 m0, s34
	s_nop 0
	global_load_lds_dwordx4 v[210:211], off
	v_lshl_add_u64 v[210:211], s[28:29], 0, v[130:131]
	s_add_i32 m0, s34, 0x2000
	s_nop 0
	global_load_lds_dwordx4 v[210:211], off
	v_lshl_add_u64 v[210:211], v[214:215], 0, s[18:19]
	s_mov_b32 m0, s40
	s_nop 0
	global_load_lds_dwordx4 v[210:211], off
	v_lshl_add_u64 v[210:211], v[216:217], 0, s[18:19]
	s_mov_b32 m0, s41
	s_nop 0
	global_load_lds_dwordx4 v[210:211], off
	s_waitcnt vmcnt(8)
	s_waitcnt lgkmcnt(0)
	s_barrier
	s_waitcnt lgkmcnt(0)
	v_mfma_f32_16x16x32_bf16 v[60:63], v[140:143], v[178:181], v[60:63]
	v_mfma_f32_16x16x32_bf16 v[56:59], v[154:157], v[178:181], v[56:59]
	v_mfma_f32_16x16x32_bf16 v[44:47], v[140:143], v[186:189], v[44:47]
	v_mfma_f32_16x16x32_bf16 v[40:43], v[154:157], v[186:189], v[40:43]
	v_mfma_f32_16x16x32_bf16 v[28:31], v[140:143], v[194:197], v[28:31]
	v_mfma_f32_16x16x32_bf16 v[24:27], v[154:157], v[194:197], v[24:27]
	v_mfma_f32_16x16x32_bf16 v[12:15], v[140:143], v[202:205], v[12:15]
	v_mfma_f32_16x16x32_bf16 v[8:11], v[154:157], v[202:205], v[8:11]
	v_mfma_f32_16x16x32_bf16 v[60:63], v[150:153], v[182:185], v[60:63]
	v_mfma_f32_16x16x32_bf16 v[56:59], v[158:161], v[182:185], v[56:59]
	v_mfma_f32_16x16x32_bf16 v[44:47], v[150:153], v[190:193], v[44:47]
	v_mfma_f32_16x16x32_bf16 v[40:43], v[158:161], v[190:193], v[40:43]
	v_mfma_f32_16x16x32_bf16 v[28:31], v[150:153], v[198:201], v[28:31]
	v_mfma_f32_16x16x32_bf16 v[24:27], v[158:161], v[198:201], v[24:27]
	v_mfma_f32_16x16x32_bf16 v[12:15], v[150:153], v[206:209], v[12:15]
	v_mfma_f32_16x16x32_bf16 v[8:11], v[158:161], v[206:209], v[8:11]
	v_mfma_f32_16x16x32_bf16 v[52:55], v[162:165], v[178:181], v[52:55]
	v_mfma_f32_16x16x32_bf16 v[48:51], v[170:173], v[178:181], v[48:51]
	v_mfma_f32_16x16x32_bf16 v[36:39], v[162:165], v[186:189], v[36:39]
	v_mfma_f32_16x16x32_bf16 v[32:35], v[170:173], v[186:189], v[32:35]
	v_mfma_f32_16x16x32_bf16 v[20:23], v[162:165], v[194:197], v[20:23]
	v_mfma_f32_16x16x32_bf16 v[16:19], v[170:173], v[194:197], v[16:19]
	v_mfma_f32_16x16x32_bf16 v[4:7], v[162:165], v[202:205], v[4:7]
	v_mfma_f32_16x16x32_bf16 v[0:3], v[170:173], v[202:205], v[0:3]
	v_mfma_f32_16x16x32_bf16 v[52:55], v[166:169], v[182:185], v[52:55]
	v_mfma_f32_16x16x32_bf16 v[48:51], v[174:177], v[182:185], v[48:51]
	v_mfma_f32_16x16x32_bf16 v[36:39], v[166:169], v[190:193], v[36:39]
	v_mfma_f32_16x16x32_bf16 v[32:35], v[174:177], v[190:193], v[32:35]
	v_mfma_f32_16x16x32_bf16 v[20:23], v[166:169], v[198:201], v[20:23]
	v_mfma_f32_16x16x32_bf16 v[16:19], v[174:177], v[198:201], v[16:19]
	v_mfma_f32_16x16x32_bf16 v[4:7], v[166:169], v[206:209], v[4:7]
	v_mfma_f32_16x16x32_bf16 v[0:3], v[174:177], v[206:209], v[0:3]
	s_barrier
	s_add_i32 s51, s51, 2
	s_add_u32 s26, s26, 0x100
	s_addc_u32 s27, s27, 0
	s_add_u32 s49, s49, 0x100
	s_addc_u32 s50, s50, 0
	s_cmpk_gt_u32 s51, 0x55
	s_cbranch_scc0 .LBB0_727
	s_and_b64 vcc, exec, s[20:21]
	s_cbranch_vccz .LBB0_730
	s_barrier
